# phase 0: the first batch's x rows requested before the narrow-weight staging (their latency runs under it)
# baseline (speedup 1.0000x reference)
.Lp0_nokm:
	v_readfirstlane_b32 s18, v196
	s_lshl_b32 s16, s96, 6
	s_lshl_b32 s18, s18, 3
	s_add_u32 s16, s16, s18
	s_lshl_b32 s18, s16, 13
	s_add_u32 s22, s4, s18
	s_addc_u32 s23, s5, 0
	s_add_u32 s32, s22, 0x1000
	s_addc_u32 s33, s23, 0
	global_load_dwordx4 v[64:67], v166, s[22:23] offset:0 nt
	global_load_dwordx4 v[68:71], v166, s[22:23] offset:1024 nt
	global_load_dwordx4 v[72:75], v166, s[22:23] offset:2048 nt
	global_load_dwordx4 v[76:79], v166, s[22:23] offset:3072 nt
	global_load_dwordx4 v[80:83], v166, s[32:33] offset:0 nt
	global_load_dwordx4 v[84:87], v166, s[32:33] offset:1024 nt
	global_load_dwordx4 v[88:91], v166, s[32:33] offset:2048 nt
	global_load_dwordx4 v[92:95], v166, s[32:33] offset:3072 nt
	s_add_u32 s22, s22, 0x2000
	s_addc_u32 s23, s23, 0
	s_add_u32 s32, s22, 0x1000
	s_addc_u32 s33, s23, 0
	global_load_dwordx4 v[96:99], v166, s[22:23] offset:0 nt
	global_load_dwordx4 v[100:103], v166, s[22:23] offset:1024 nt
	global_load_dwordx4 v[104:107], v166, s[22:23] offset:2048 nt
	global_load_dwordx4 v[108:111], v166, s[22:23] offset:3072 nt
	global_load_dwordx4 v[112:115], v166, s[32:33] offset:0 nt
	global_load_dwordx4 v[116:119], v166, s[32:33] offset:1024 nt
	global_load_dwordx4 v[120:123], v166, s[32:33] offset:2048 nt
	global_load_dwordx4 v[124:127], v166, s[32:33] offset:3072 nt
	v_lshrrev_b32_e32 v0, 2, v198
	s_mov_b32 s20, 0xc040
	v_mul_lo_u32 v0, v0, s20
	v_and_b32_e32 v1, 3, v198
	v_lshl_add_u32 v0, v1, 4, v0
	s_add_u32 s18, s10, 0x4000
	s_addc_u32 s19, s11, 0
	global_load_dwordx4 v[4:7], v0, s[18:19]
	s_add_u32 s18, s18, 0x602000
	s_addc_u32 s19, s19, 0
	global_load_dwordx4 v[8:11], v0, s[18:19]
	s_add_u32 s18, s18, 0x602000
	s_addc_u32 s19, s19, 0
	global_load_dwordx4 v[12:15], v0, s[18:19]
	s_add_u32 s18, s18, 0x602000
	s_addc_u32 s19, s19, 0
	global_load_dwordx4 v[16:19], v0, s[18:19]
	s_add_u32 s18, s18, 0x602000
	s_addc_u32 s19, s19, 0
	global_load_dwordx4 v[20:23], v0, s[18:19]
	s_add_u32 s18, s18, 0x602000
	s_addc_u32 s19, s19, 0
	global_load_dwordx4 v[24:27], v0, s[18:19]
	s_add_u32 s18, s18, 0x602000
	s_addc_u32 s19, s19, 0
	global_load_dwordx4 v[28:31], v0, s[18:19]
	s_add_u32 s18, s18, 0x602000
	s_addc_u32 s19, s19, 0
	global_load_dwordx4 v[32:35], v0, s[18:19]
	s_add_u32 s18, s18, 0x602000
	s_addc_u32 s19, s19, 0
	global_load_dwordx4 v[36:39], v0, s[18:19]
	s_add_u32 s18, s18, 0x602000
	s_addc_u32 s19, s19, 0
	global_load_dwordx4 v[40:43], v0, s[18:19]
	s_add_u32 s18, s18, 0x602000
	s_addc_u32 s19, s19, 0
	global_load_dwordx4 v[44:47], v0, s[18:19]
	s_add_u32 s18, s18, 0x602000
	s_addc_u32 s19, s19, 0
	global_load_dwordx4 v[48:51], v0, s[18:19]
	s_add_u32 s18, s18, 0x602000
	s_addc_u32 s19, s19, 0
	global_load_dwordx4 v[52:55], v0, s[18:19]
	s_add_u32 s18, s18, 0x602000
	s_addc_u32 s19, s19, 0
	global_load_dwordx4 v[56:59], v0, s[18:19]
	s_add_u32 s18, s18, 0x602000
	s_addc_u32 s19, s19, 0
	global_load_dwordx4 v[60:63], v0, s[18:19]
	s_add_u32 s18, s18, 0x602000
	s_addc_u32 s19, s19, 0
	global_load_dwordx4 v[128:131], v0, s[18:19]
	s_add_u32 s32, s8, 0x1000
	s_addc_u32 s33, s9, 0
	global_load_dwordx4 v[200:203], v166, s[8:9] offset:0
	global_load_dwordx4 v[204:207], v166, s[8:9] offset:1024
	global_load_dwordx4 v[208:211], v166, s[8:9] offset:2048
	global_load_dwordx4 v[212:215], v166, s[8:9] offset:3072
	global_load_dwordx4 v[216:219], v166, s[32:33] offset:0
	global_load_dwordx4 v[220:223], v166, s[32:33] offset:1024
	global_load_dwordx4 v[224:227], v166, s[32:33] offset:2048
	global_load_dwordx4 v[228:231], v166, s[32:33] offset:3072
	v_bfe_u32 v2, v198, 2, 2
	v_lshrrev_b32_e32 v3, 4, v198
	v_lshl_add_u32 v2, v2, 6, v3
	v_lshlrev_b32_e32 v2, 6, v2
	v_add_u32_e32 v3, v1, v196
	v_and_b32_e32 v3, 3, v3
	v_lshl_add_u32 v2, v3, 4, v2
	s_waitcnt vmcnt(23)
	ds_write_b128 v2, v[4:7] offset:0
	s_waitcnt vmcnt(22)
	ds_write_b128 v2, v[8:11] offset:2048
	s_waitcnt vmcnt(21)
	ds_write_b128 v2, v[12:15] offset:16384
	s_waitcnt vmcnt(20)
	ds_write_b128 v2, v[16:19] offset:18432
	s_waitcnt vmcnt(19)
	ds_write_b128 v2, v[20:23] offset:32768
	s_waitcnt vmcnt(18)
	ds_write_b128 v2, v[24:27] offset:34816
	s_waitcnt vmcnt(17)
	ds_write_b128 v2, v[28:31] offset:49152
	s_waitcnt vmcnt(16)
	ds_write_b128 v2, v[32:35] offset:51200
	s_waitcnt vmcnt(15)
	v_add_u32_e32 v3, 0x10000, v2
	ds_write_b128 v3, v[36:39] offset:0
	s_waitcnt vmcnt(14)
	ds_write_b128 v3, v[40:43] offset:2048
	s_waitcnt vmcnt(13)
	ds_write_b128 v3, v[44:47] offset:16384
	s_waitcnt vmcnt(12)
	ds_write_b128 v3, v[48:51] offset:18432
	s_waitcnt vmcnt(11)
	ds_write_b128 v3, v[52:55] offset:32768
	s_waitcnt vmcnt(10)
	ds_write_b128 v3, v[56:59] offset:34816
	s_waitcnt vmcnt(9)
	ds_write_b128 v3, v[60:63] offset:49152
	s_waitcnt vmcnt(8)
	ds_write_b128 v3, v[128:131] offset:51200
	v_lshrrev_b32_e32 v0, 2, v197
	v_add_u32_e32 v1, 0, v0
	v_and_b32_e32 v1, 3, v1
	v_lshlrev_b32_e32 v1, 4, v1
	v_lshl_add_u32 v244, v197, 6, v1
	v_add_u32_e32 v248, 0x10000, v244
	v_add_u32_e32 v1, 1, v0
	v_and_b32_e32 v1, 3, v1
	v_lshlrev_b32_e32 v1, 4, v1
	v_lshl_add_u32 v245, v197, 6, v1
	v_add_u32_e32 v249, 0x10000, v245
	v_add_u32_e32 v1, 2, v0
	v_and_b32_e32 v1, 3, v1
	v_lshlrev_b32_e32 v1, 4, v1
	v_lshl_add_u32 v246, v197, 6, v1
	v_add_u32_e32 v250, 0x10000, v246
	v_add_u32_e32 v1, 3, v0
	v_and_b32_e32 v1, 3, v1
	v_lshlrev_b32_e32 v1, 4, v1
	v_lshl_add_u32 v247, v197, 6, v1
	v_add_u32_e32 v251, 0x10000, v247
	v_and_b32_e32 v0, 32, v197
	v_cmp_ne_u32_e64 s[24:25], 0, v0
	v_and_b32_e32 v0, 16, v197
	v_cmp_ne_u32_e64 s[26:27], 0, v0
	v_and_b32_e32 v0, 8, v197
	v_cmp_ne_u32_e64 s[28:29], 0, v0
	v_and_b32_e32 v0, 4, v197
	v_cmp_ne_u32_e64 s[30:31], 0, v0
	v_and_b32_e32 v0, 2, v197
	v_cmp_ne_u32_e64 s[34:35], 0, v0
	v_bfe_u32 v0, v197, 1, 3
	v_lshlrev_b32_e32 v0, 2, v0
	global_load_dword v237, v0, s[36:37]
	global_load_dword v195, v0, s[38:39]
	s_waitcnt vmcnt(0) lgkmcnt(0)
	v_mul_f32_e32 v237, 0x3fb8aa3b, v237
	v_exp_f32_e32 v237, v237
	s_mov_b32 s20, 0x3a000000
	s_barrier
	s_mov_b32 s17, 0
